# static priority (strategy 4): waves 4-7 run the FoX prompt key-tile loop at s_setprio 1, reset at loop exit
# speedup vs baseline: 1.0112x; 1.0112x over previous
; #define GAS __attribute__((address_space(1)))
; #define AT_LOAD(t) do { _Pragma("unroll") for (int i_ = 0; i_ < 2; ++i_) { const int c_ = tid + 512 * i_, row_ = c_ >> 4, ch_ = c_ & 15; \
;         kr[i_] = *(const GAS u32x4*)(Kg + (size_t)(64 * (t) + row_) * NP + ch_ * 8); vr[i_] = *(const GAS u32x4*)(Vg + (size_t)(64 * (t) + row_) * NP + ch_ * 8); } } while (0)
; #define AT_STORE(buf) do { _Pragma("unroll") for (int i_ = 0; i_ < 2; ++i_) { const int c_ = tid + 512 * i_, row_ = c_ >> 4, ch_ = c_ & 15; \
;         *(LAS u32x4*)(L + AT_K + (buf) * 17408 + row_ * 272 + ch_ * 16) = kr[i_]; *(LAS u32x4*)(L + AT_V + (buf) * 20480 + row_ * AVP + ch_ * 16) = vr[i_]; } } while (0)
; __device__ __forceinline__ void fox_prompt_unit(LAS char* L, const bf16_t* P, const float* lfT, bf16_t* MIX, int b, int h, int qb, const int wv) {
;     ...
;     const bf16_t* Kg = P + rowb * NP + PC_KB + h * 128; const bf16_t* Vg = P + rowb * NP + PC_VB + h * 128;
;     u32x4 kr[2], vr[2];
;     ...
;     bf16x8 qf[8];
;     { const bf16_t* Qg = P + (rowb + 256 * qb + 32 * wid + r32) * NP + PC_QB + h * 128 + 8 * hi;
; #pragma unroll
;         for (int kk = 0; kk < 8; ++kk) qf[kk] = *(const GAS bf16x8*)(Qg + 16 * kk); }
;     f32x16 o[4];
; #pragma unroll
;     for (int d = 0; d < 4; ++d)
; #pragma unroll
;         for (int r = 0; r < 16; ++r) o[d][r] = 0.f;
;     float m = -INFINITY, l = 0.f;
;     AT_LOAD(0); AT_STORE(0);
;     __syncthreads();
;     for (int t = 0; t < NT; ++t) {
;         if (t + 1 < NT) AT_LOAD(t + 1);
.LBB0_196:
	s_or_b64 exec, exec, s[0:1]
	s_lshl_b32 s7, s7, 2
	s_lshl_b32 s0, s6, 12
	s_mul_i32 s6, s6, 0x3000000
	s_add_u32 s1, s20, s6
	s_addc_u32 s14, s21, 0
	s_lshl_b32 s8, s15, 8
	s_sub_i32 s0, s0, s8
	s_lshl_b32 s9, s9, 5
	s_lshl_b32 s6, s2, 7
	s_addk_i32 s0, 0xf00
	s_ashr_i32 s16, s9, 31
	s_add_u32 s17, s9, s0
	s_addc_u32 s16, s16, 0
	s_lshl_b32 s2, s2, 8
	s_add_u32 s0, s1, s2
	v_and_b32_e32 v2, 0x78, v10
	s_addc_u32 s1, s14, 0
	v_lshlrev_b32_e32 v2, 1, v2
	v_mov_b32_e32 v3, v1
	v_lshl_add_u64 v[2:3], s[0:1], 0, v[2:3]
	s_mov_b64 s[0:1], 0x2000
	v_lshl_add_u64 v[154:155], v[2:3], 0, s[0:1]
	s_mov_b64 s[0:1], 0x2800
	v_ashrrev_i32_e32 v6, 4, v0
	v_add_u32_e32 v0, 0x200, v0
	v_lshl_add_u64 v[156:157], v[2:3], 0, s[0:1]
	v_mad_i64_i32 v[2:3], s[0:1], v6, s63, v[154:155]
	v_ashrrev_i32_e32 v7, 4, v0
	v_mad_i64_i32 v[4:5], s[0:1], v6, s63, v[156:157]
	global_load_dwordx4 v[98:101], v[2:3], off
	global_load_dwordx4 v[102:105], v[4:5], off
	v_mad_i64_i32 v[2:3], s[0:1], v7, s63, v[154:155]
	v_and_b32_e32 v9, 31, v14
	v_mad_i64_i32 v[4:5], s[0:1], v7, s63, v[156:157]
	global_load_dwordx4 v[106:109], v[2:3], off
	global_load_dwordx4 v[110:113], v[4:5], off
	v_or_b32_e32 v152, s17, v9
	v_mov_b64_e32 v[2:3], s[20:21]
	v_mad_u64_u32 v[2:3], s[0:1], v152, s63, v[2:3]
	v_mov_b32_e32 v0, 0x3000
	v_lshrrev_b32_e32 v8, 5, v8
	v_mad_i32_i24 v3, s16, v0, v3
	v_lshl_add_u64 v[2:3], v[2:3], 0, s[2:3]
	v_lshlrev_b32_e32 v0, 4, v8
	v_lshl_add_u64 v[2:3], v[2:3], 0, v[0:1]
	s_mov_b64 s[0:1], 0x1800
	v_lshl_add_u64 v[4:5], v[2:3], 0, s[0:1]
	v_add_co_u32_e32 v2, vcc, s60, v2
	v_lshlrev_b32_e32 v164, 2, v8
	s_nop 0
	v_addc_co_u32_e32 v3, vcc, 0, v3, vcc
	global_load_dwordx4 v[114:117], v[4:5], off offset:32
	global_load_dwordx4 v[118:121], v[4:5], off offset:64
	global_load_dwordx4 v[122:125], v[4:5], off offset:96
	global_load_dwordx4 v[126:129], v[4:5], off offset:128
	global_load_dwordx4 v[130:133], v[4:5], off offset:160
	global_load_dwordx4 v[134:137], v[4:5], off offset:192
	global_load_dwordx4 v[138:141], v[2:3], off offset:2048
	global_load_dwordx4 v[142:145], v[4:5], off offset:224
	v_lshlrev_b32_e32 v3, 4, v14
	v_and_b32_e32 v2, 16, v14
	v_lshrrev_b32_e32 v4, 2, v14
	v_lshlrev_b32_e32 v5, 2, v14
	v_and_b32_e32 v3, 0xf0, v3
	v_mul_lo_u32 v165, v6, s56
	v_mul_lo_u32 v166, v6, s18
	v_mul_u32_u24_e32 v8, 0x110, v9
	v_and_or_b32 v2, v5, 12, v2
	v_add_u32_e32 v167, 0, v3
	v_mul_lo_u32 v168, v7, s56
	v_mul_lo_u32 v169, v7, s18
	v_and_or_b32 v3, v4, 3, v164
	v_lshlrev_b32_e32 v2, 1, v2
	v_add3_u32 v170, 0, v8, v0
	v_add_u32_e32 v4, v167, v165
	v_add_u32_e32 v5, v167, v166
	v_add_u32_e32 v8, v167, v168
	v_add_u32_e32 v10, v167, v169
	v_mul_u32_u24_e32 v3, 0x140, v3
	s_add_i32 s0, 0, 0x12800
	v_mov_b32_e32 v14, v1
	v_mov_b32_e32 v15, v1
	v_or_b32_e32 v171, s9, v9
	v_add3_u32 v172, 0, v3, v2
	v_add_u32_e32 v173, s0, v0
	v_add_u32_e32 v175, 64, v7
	v_add_u32_e32 v176, 64, v6
	v_mov_b32_e32 v0, v1
	v_mov_b32_e32 v2, v1
	v_mov_b32_e32 v3, v1
	v_mov_b32_e32 v6, v1
	v_mov_b32_e32 v7, v1
	v_mov_b32_e32 v9, v1
	v_mov_b32_e32 v11, v1
	v_mov_b32_e32 v12, v1
	v_mov_b32_e32 v13, v1
	s_waitcnt vmcnt(11)
	ds_write_b128 v4, v[98:101]
	s_waitcnt vmcnt(10)
	ds_write_b128 v5, v[102:105] offset:34816
	s_waitcnt vmcnt(9)
	ds_write_b128 v8, v[106:109]
	s_waitcnt vmcnt(8)
	ds_write_b128 v10, v[110:113] offset:34816
	v_mov_b32_e32 v4, v1
	v_mov_b32_e32 v5, v1
	v_mov_b32_e32 v8, v1
	v_mov_b32_e32 v10, v1
	v_mov_b64_e32 v[64:65], v[14:15]
	v_mov_b64_e32 v[48:49], v[14:15]
	v_mov_b64_e32 v[32:33], v[14:15]
	s_lshl_b32 s0, s15, 2
	v_mov_b64_e32 v[62:63], v[12:13]
	v_mov_b64_e32 v[60:61], v[10:11]
	v_mov_b64_e32 v[58:59], v[8:9]
	v_mov_b64_e32 v[56:57], v[6:7]
	v_mov_b64_e32 v[54:55], v[4:5]
	v_mov_b64_e32 v[52:53], v[2:3]
	v_mov_b64_e32 v[50:51], v[0:1]
	v_mov_b64_e32 v[46:47], v[12:13]
	v_mov_b64_e32 v[44:45], v[10:11]
	v_mov_b64_e32 v[42:43], v[8:9]
	v_mov_b64_e32 v[40:41], v[6:7]
	v_mov_b64_e32 v[38:39], v[4:5]
	v_mov_b64_e32 v[36:37], v[2:3]
	v_mov_b64_e32 v[34:35], v[0:1]
	v_mov_b64_e32 v[30:31], v[12:13]
	v_mov_b64_e32 v[28:29], v[10:11]
	v_mov_b64_e32 v[26:27], v[8:9]
	v_mov_b64_e32 v[24:25], v[6:7]
	v_mov_b64_e32 v[22:23], v[4:5]
	v_mov_b64_e32 v[20:21], v[2:3]
	v_mov_b64_e32 v[18:19], v[0:1]
	v_mov_b64_e32 v[16:17], v[14:15]
	s_mov_b32 s2, 0
	v_mov_b32_e32 v153, s16
	s_or_b32 s14, s9, 31
	v_or_b32_e32 v174, s8, v164
	s_sub_i32 s15, s0, 64
	v_mov_b32_e32 v177, 0
	v_mov_b32_e32 v158, 0xff800000
	v_mov_b64_e32 v[14:15], v[12:13]
	v_mov_b64_e32 v[12:13], v[10:11]
	v_mov_b64_e32 v[10:11], v[8:9]
	v_mov_b64_e32 v[8:9], v[6:7]
	v_mov_b64_e32 v[6:7], v[4:5]
	v_mov_b64_e32 v[4:5], v[2:3]
	v_mov_b64_e32 v[2:3], v[0:1]
	s_mov_b32 s17, 0
	s_waitcnt vmcnt(0) lgkmcnt(0)
	s_barrier
	s_cmpk_lt_i32 s73, 0xff40
	s_cbranch_scc0 .Lfp_noprio
	s_setprio 1
.Lfp_noprio:
.LBB0_197:
	s_add_i32 s16, s17, 1
	s_cmp_lt_u32 s16, s7
	s_cselect_b64 s[0:1], -1, 0
	s_cmp_ge_u32 s16, s7
	s_cbranch_scc1 .LBB0_199
	v_add_u32_e32 v0, s2, v176
	v_mad_i64_i32 v[66:67], s[22:23], v0, s63, v[154:155]
	v_mad_i64_i32 v[68:69], s[22:23], v0, s63, v[156:157]
	v_add_u32_e32 v0, s2, v175
	global_load_dwordx4 v[98:101], v[66:67], off
	global_load_dwordx4 v[102:105], v[68:69], off
	v_mad_i64_i32 v[66:67], s[22:23], v0, s63, v[154:155]
	v_mad_i64_i32 v[68:69], s[22:23], v0, s63, v[156:157]
	global_load_dwordx4 v[106:109], v[66:67], off
	global_load_dwordx4 v[110:113], v[68:69], off

; #define GAS __attribute__((address_space(1)))
; __device__ __forceinline__ unsigned pkbf(float lo, float hi) { f32x2 v = {lo, hi}; bf16x2_t b = __builtin_convertvector(v, bf16x2_t); return __builtin_bit_cast(unsigned, b); }
; __device__ __forceinline__ float xsum32(float x) { auto rr = __builtin_amdgcn_permlane32_swap(__float_as_uint(x), __float_as_uint(x), false, false); return __uint_as_float(rr[0]) + __uint_as_float(rr[1]); }
; __device__ __forceinline__ void fox_prompt_unit(LAS char* L, const bf16_t* P, const float* lfT, bf16_t* MIX, int b, int h, int qb, const int wv) {
;     ...
;     l = xsum32(l);
;     const float inv = 1.0f / l;
;     bf16_t* Og = MIX + (rowb + 256 * qb + 32 * wid + r32) * DM + 1024 + h * 128 + 4 * hi;
; #pragma unroll
;     for (int d = 0; d < 4; ++d)
; #pragma unroll
;         for (int g = 0; g < 4; ++g) { u32x2 w; w.x = pkbf(o[d][4 * g] * inv, o[d][4 * g + 1] * inv); w.y = pkbf(o[d][4 * g + 2] * inv, o[d][4 * g + 3] * inv);
;             *(GAS u32x2*)(Og + 32 * d + 8 * g) = w; }
.LBB0_207:
	s_setprio 0
	v_mov_b32_e32 v0, v177
	s_nop 1
	v_permlane32_swap_b32_e32 v177, v0
	v_add_f32_e32 v0, v177, v0
	v_div_scale_f32 v66, s[0:1], v0, v0, 1.0
	v_rcp_f32_e32 v67, v66
	v_readlane_b32 s0, v250, 29
	v_readlane_b32 s1, v250, 30
	s_lshl_b32 s2, s6, 1
	v_fma_f32 v68, -v66, v67, 1.0
	v_fmac_f32_e32 v67, v68, v67
	v_div_scale_f32 v68, vcc, 1.0, v0, 1.0
	v_mul_f32_e32 v69, v68, v67
	v_fma_f32 v70, -v66, v69, v68
	v_fmac_f32_e32 v69, v70, v67
	v_fma_f32 v66, -v66, v69, v68
	v_div_fmas_f32 v66, v66, v67, v69
	v_lshlrev_b64 v[68:69], 12, v[152:153]
	v_div_fixup_f32 v66, v66, v0, 1.0
	v_lshl_add_u64 v[68:69], s[0:1], 0, v[68:69]
	v_lshl_add_u64 v[68:69], v[68:69], 0, s[2:3]
	v_lshlrev_b32_e32 v0, 1, v164
	v_pk_mul_f32 v[50:51], v[50:51], v[66:67] op_sel_hi:[1,0]
	v_pk_mul_f32 v[52:53], v[52:53], v[66:67] op_sel_hi:[1,0]
	v_pk_mul_f32 v[34:35], v[34:35], v[66:67] op_sel_hi:[1,0]
	v_pk_mul_f32 v[36:37], v[36:37], v[66:67] op_sel_hi:[1,0]
	v_pk_mul_f32 v[18:19], v[18:19], v[66:67] op_sel_hi:[1,0]
	v_pk_mul_f32 v[20:21], v[20:21], v[66:67] op_sel_hi:[1,0]
	v_pk_mul_f32 v[2:3], v[2:3], v[66:67] op_sel_hi:[1,0]
	v_pk_mul_f32 v[4:5], v[4:5], v[66:67] op_sel_hi:[1,0]
	v_lshl_add_u64 v[68:69], v[68:69], 0, v[0:1]
	v_cvt_pk_bf16_f32 v50, v50, v51
	v_cvt_pk_bf16_f32 v51, v52, v53
	v_cvt_pk_bf16_f32 v34, v34, v35
	v_cvt_pk_bf16_f32 v35, v36, v37
	v_cvt_pk_bf16_f32 v18, v18, v19
	v_cvt_pk_bf16_f32 v19, v20, v21
	v_cvt_pk_bf16_f32 v2, v2, v3
	v_cvt_pk_bf16_f32 v3, v4, v5
	global_store_dwordx2 v[68:69], v[50:51], off offset:2048
	v_pk_mul_f32 v[50:51], v[54:55], v[66:67] op_sel_hi:[1,0]
	v_pk_mul_f32 v[52:53], v[56:57], v[66:67] op_sel_hi:[1,0]
	global_store_dwordx2 v[68:69], v[34:35], off offset:2112
	v_pk_mul_f32 v[34:35], v[38:39], v[66:67] op_sel_hi:[1,0]
	v_pk_mul_f32 v[36:37], v[40:41], v[66:67] op_sel_hi:[1,0]
	global_store_dwordx2 v[68:69], v[18:19], off offset:2176
	v_pk_mul_f32 v[18:19], v[22:23], v[66:67] op_sel_hi:[1,0]
	v_pk_mul_f32 v[20:21], v[24:25], v[66:67] op_sel_hi:[1,0]
	global_store_dwordx2 v[68:69], v[2:3], off offset:2240
	v_pk_mul_f32 v[2:3], v[6:7], v[66:67] op_sel_hi:[1,0]
	v_pk_mul_f32 v[4:5], v[8:9], v[66:67] op_sel_hi:[1,0]
	v_cvt_pk_bf16_f32 v50, v50, v51
	v_cvt_pk_bf16_f32 v51, v52, v53
	v_cvt_pk_bf16_f32 v34, v34, v35
	v_cvt_pk_bf16_f32 v35, v36, v37
	v_cvt_pk_bf16_f32 v18, v18, v19
	v_cvt_pk_bf16_f32 v19, v20, v21
	v_cvt_pk_bf16_f32 v2, v2, v3
	v_cvt_pk_bf16_f32 v3, v4, v5
	global_store_dwordx2 v[68:69], v[50:51], off offset:2064
	v_pk_mul_f32 v[50:51], v[58:59], v[66:67] op_sel_hi:[1,0]
	v_pk_mul_f32 v[52:53], v[60:61], v[66:67] op_sel_hi:[1,0]
	global_store_dwordx2 v[68:69], v[34:35], off offset:2128
	v_pk_mul_f32 v[34:35], v[42:43], v[66:67] op_sel_hi:[1,0]
	v_pk_mul_f32 v[36:37], v[44:45], v[66:67] op_sel_hi:[1,0]
	global_store_dwordx2 v[68:69], v[18:19], off offset:2192
	v_pk_mul_f32 v[18:19], v[26:27], v[66:67] op_sel_hi:[1,0]
	v_pk_mul_f32 v[20:21], v[28:29], v[66:67] op_sel_hi:[1,0]
	global_store_dwordx2 v[68:69], v[2:3], off offset:2256
	v_pk_mul_f32 v[2:3], v[10:11], v[66:67] op_sel_hi:[1,0]
	v_pk_mul_f32 v[4:5], v[12:13], v[66:67] op_sel_hi:[1,0]
	v_cvt_pk_bf16_f32 v50, v50, v51
	v_cvt_pk_bf16_f32 v51, v52, v53
	v_cvt_pk_bf16_f32 v34, v34, v35
	v_cvt_pk_bf16_f32 v35, v36, v37
	v_cvt_pk_bf16_f32 v18, v18, v19
	v_cvt_pk_bf16_f32 v19, v20, v21
	v_cvt_pk_bf16_f32 v2, v2, v3
	v_cvt_pk_bf16_f32 v3, v4, v5
	global_store_dwordx2 v[68:69], v[50:51], off offset:2080
	v_pk_mul_f32 v[50:51], v[62:63], v[66:67] op_sel_hi:[1,0]
	v_pk_mul_f32 v[52:53], v[64:65], v[66:67] op_sel_hi:[1,0]
	global_store_dwordx2 v[68:69], v[34:35], off offset:2144
	v_pk_mul_f32 v[34:35], v[46:47], v[66:67] op_sel_hi:[1,0]
	v_pk_mul_f32 v[36:37], v[48:49], v[66:67] op_sel_hi:[1,0]
	global_store_dwordx2 v[68:69], v[18:19], off offset:2208
	v_pk_mul_f32 v[18:19], v[30:31], v[66:67] op_sel_hi:[1,0]
	v_pk_mul_f32 v[20:21], v[32:33], v[66:67] op_sel_hi:[1,0]
	global_store_dwordx2 v[68:69], v[2:3], off offset:2272
	v_pk_mul_f32 v[2:3], v[14:15], v[66:67] op_sel_hi:[1,0]
	v_pk_mul_f32 v[4:5], v[16:17], v[66:67] op_sel_hi:[1,0]
	v_cvt_pk_bf16_f32 v50, v50, v51
	v_cvt_pk_bf16_f32 v51, v52, v53
	v_cvt_pk_bf16_f32 v34, v34, v35
	v_cvt_pk_bf16_f32 v35, v36, v37
	v_cvt_pk_bf16_f32 v18, v18, v19
	v_cvt_pk_bf16_f32 v19, v20, v21
	v_cvt_pk_bf16_f32 v2, v2, v3
	v_cvt_pk_bf16_f32 v3, v4, v5
	global_store_dwordx2 v[68:69], v[50:51], off offset:2096
	global_store_dwordx2 v[68:69], v[34:35], off offset:2160
	global_store_dwordx2 v[68:69], v[18:19], off offset:2224
	global_store_dwordx2 v[68:69], v[2:3], off offset:2288
	s_mov_b64 s[0:1], 0
